# attention: first four K reads of each step issued in front of the step barrier, vmcnt(5)->vmcnt(2) so K lands one barrier earlier
# baseline (speedup 1.0000x reference)
.LBB0_961:
	s_waitcnt vmcnt(2)
	s_barrier
	s_mov_b32 s19, s5
	s_mov_b32 s5, s25
	s_mul_i32 s9, s25, 0x6000
	s_add_i32 s25, s9, 0
	v_add_u32_e32 v124, s25, v225
	ds_read_b128 v[120:123], v124
	ds_read_b128 v[160:163], v124 offset:4096
	ds_read_b128 v[168:171], v124 offset:8192
	ds_read_b128 v[172:175], v124 offset:12288
.Lmy_att_head2:
	v_exp_f32_e32 v188, v148
	v_exp_f32_e32 v189, v149
	v_exp_f32_e32 v194, v150
	v_exp_f32_e32 v195, v151
	s_waitcnt lgkmcnt(3)
	v_mfma_f32_16x16x32_bf16 v[124:127], v[120:123], v[4:7], v[48:51]
	v_mfma_f32_16x16x32_bf16 v[120:123], v[120:123], v[40:43], v[52:55]
	v_add_u32_e32 v196, s25, v234
	ds_read_b128 v[184:187], v196
	s_waitcnt lgkmcnt(3)
	v_mfma_f32_16x16x32_bf16 v[148:151], v[160:163], v[4:7], v[48:51]
	v_add_f32_e32 v180, v157, v156
	v_add_f32_e32 v181, v145, v144
	v_mfma_f32_16x16x32_bf16 v[160:163], v[160:163], v[40:43], v[52:55]
	ds_read_b128 v[176:179], v196 offset:4096
	s_waitcnt lgkmcnt(3)
	v_mfma_f32_16x16x32_bf16 v[164:167], v[168:171], v[4:7], v[48:51]
	v_exp_f32_e32 v190, v140
	v_exp_f32_e32 v191, v141
	v_add_f32_e32 v206, v158, v180
	v_mfma_f32_16x16x32_bf16 v[168:171], v[168:171], v[40:43], v[52:55]
	v_add_f32_e32 v207, v146, v181
	ds_read_b128 v[180:183], v196 offset:8192
	v_exp_f32_e32 v192, v142
	v_exp_f32_e32 v193, v143
	s_waitcnt lgkmcnt(3)
	v_mfma_f32_16x16x32_bf16 v[140:143], v[172:175], v[4:7], v[48:51]
	v_add_f32_e32 v206, v159, v206
	v_add_f32_e32 v207, v147, v207
	v_mfma_f32_16x16x32_bf16 v[172:175], v[172:175], v[40:43], v[52:55]
	s_add_i32 s9, s4, -1
	s_cmp_ge_u32 s9, s2
	s_cbranch_scc1 .LBB0_963
	s_add_u32 s9, s6, s30
	s_addc_u32 s35, s7, s31
	s_add_u32 s34, s9, 0x180000
	s_addc_u32 s35, s35, 0
	s_add_u32 s36, s10, 0xffffe000
	s_mul_i32 s9, s8, 0x6000
	s_addc_u32 s37, s11, -1
	s_add_i32 s9, s9, 0
	s_add_i32 s48, s9, s77
	s_mov_b32 m0, s48
	s_add_i32 s9, s9, s97
	global_load_lds_dwordx4 v227, s[34:35]
	s_add_i32 m0, s48, 0x400
	s_nop 0
	global_load_lds_dwordx4 v229, s[34:35]
	s_add_i32 m0, s9, 0x4000
	s_nop 0
	global_load_lds_dwordx4 v232, s[36:37]

.LBB0_969:
	s_mul_i32 s34, s19, 0x6000
	s_add_i32 s49, s34, 0
	v_add_u32_e32 v164, s49, v225
	ds_read_b128 v[160:163], v164
	ds_read_b128 v[168:171], v164 offset:4096
	ds_read_b128 v[184:187], v164 offset:8192
	ds_read_b128 v[246:249], v164 offset:12288
	s_waitcnt vmcnt(2)
	s_barrier
	v_exp_f32_e32 v235, v140
	v_exp_f32_e32 v236, v141
	v_exp_f32_e32 v241, v142
	v_exp_f32_e32 v242, v143
	s_waitcnt lgkmcnt(3)
	v_mfma_f32_16x16x32_bf16 v[164:167], v[160:163], v[4:7], v[120:123]
	v_mfma_f32_16x16x32_bf16 v[160:163], v[160:163], v[40:43], v[124:127]
	v_add_u32_e32 v243, s49, v234
	ds_read_b128 v[192:195], v243
	s_waitcnt lgkmcnt(3)
	v_mfma_f32_16x16x32_bf16 v[180:183], v[168:171], v[4:7], v[120:123]
	v_add_f32_e32 v140, v153, v152
	v_mfma_f32_16x16x32_bf16 v[172:175], v[168:171], v[40:43], v[124:127]
	v_add_f32_e32 v141, v145, v144
	ds_read_b128 v[188:191], v243 offset:4096
	v_exp_f32_e32 v237, v136
	v_exp_f32_e32 v238, v137
	s_waitcnt lgkmcnt(3)
	v_mfma_f32_16x16x32_bf16 v[176:179], v[184:187], v[4:7], v[120:123]
	v_add_f32_e32 v136, v154, v140
	v_add_f32_e32 v137, v146, v141
	v_mfma_f32_16x16x32_bf16 v[140:143], v[184:187], v[40:43], v[124:127]
	ds_read_b128 v[184:187], v243 offset:8192
	v_exp_f32_e32 v239, v138
	v_exp_f32_e32 v240, v139
	s_waitcnt lgkmcnt(3)
	v_mfma_f32_16x16x32_bf16 v[168:171], v[246:249], v[4:7], v[120:123]
	v_add_f32_e32 v245, v155, v136
	v_add_f32_e32 v244, v147, v137
	v_mfma_f32_16x16x32_bf16 v[136:139], v[246:249], v[40:43], v[124:127]
	s_cmp_ge_u32 s4, s2
	s_cselect_b64 s[34:35], -1, 0
	s_and_b64 vcc, exec, s[34:35]
	s_cbranch_vccnz .LBB0_971
	s_add_u32 s65, s6, s30
	s_addc_u32 s69, s7, s31
	s_add_u32 s70, s65, 0x200000
	s_addc_u32 s71, s69, 0
	s_add_i32 s65, s25, s77
	s_mov_b64 s[80:81], s[10:11]
	s_mov_b32 m0, s65
	s_add_i32 s25, s25, s97
	global_load_lds_dwordx4 v227, s[70:71]
	s_add_i32 m0, s65, 0x400
	s_nop 0
	global_load_lds_dwordx4 v229, s[70:71]
	s_add_i32 m0, s25, 0x4000
	s_nop 0
	global_load_lds_dwordx4 v232, s[80:81]

.LBB0_977:
	s_add_u32 s30, s30, 0x100000
	s_addc_u32 s31, s31, 0
	v_pk_fma_f32 v[160:161], v[200:201], v[204:205], v[206:207]
	s_add_u32 s10, s10, 0x4000
	v_pk_fma_f32 v[200:201], v[160:161], v[208:209], v[194:195]
	s_addc_u32 s11, s11, 0
	s_add_i32 s4, s4, 2
	s_and_b64 vcc, exec, s[34:35]
	s_cbranch_vccnz .LBB0_979
	s_mov_b32 s25, s8
	s_mov_b32 s8, s19
	v_mov_b32_e32 v204, v192
	v_mov_b32_e32 v205, v193
	s_mul_i32 s9, s25, 0x6000
	v_add_u32_e32 v124, s9, v225
	ds_read_b128 v[120:123], v124
	ds_read_b128 v[160:163], v124 offset:4096
	ds_read_b128 v[168:171], v124 offset:8192
	ds_read_b128 v[172:175], v124 offset:12288
	s_waitcnt vmcnt(2)
	s_barrier
	s_mov_b32 s19, s5
	s_mov_b32 s5, s25
	s_add_i32 s25, s9, 0
	s_branch .Lmy_att_head2
